# memory cross-attention unit: redundant trailing barrier dropped
# speedup vs baseline: 1.0041x; 1.0041x over previous
; #define LAS __attribute__((address_space(3)))
; #define ATT_LSTORE(buf) do { LAS unsigned char* b_ = lds + (buf) * BUF; \
;         _Pragma("unroll") for (int i = 0; i < KPT; ++i) { if (KCH % NTHREADS == 0 || tid + i * NTHREADS < KCH) *(LAS u32x4*)(b_ + klo[i]) = kreg[i]; } \
;         _Pragma("unroll") for (int i = 0; i < VPT; ++i) *(LAS u32x4*)(b_ + vlo[i]) = vreg[i]; } while (0)
; template <int DQK, int DV, int FLAGS, int qp, int kp, int vts, int op> ...
;     ...
;             f32x2 rs2 = {0.f, 0.f};
; #pragma unroll
;             for (int r = 0; r < 16; ++r) { p0[r] = __builtin_amdgcn_exp2f(p0[r]); p1[r] = __builtin_amdgcn_exp2f(p1[r]); }
; #pragma unroll
;             for (int r = 0; r < 16; r += 2) { rs2 += (f32x2){p0[r], p0[r + 1]}; rs2 += (f32x2){p1[r], p1[r + 1]}; }
;             l += rs2.x + rs2.y;
;             bf16x8 pf[4];
;             pf[0] = pack_bf16x8(p0, 0); pf[1] = pack_bf16x8(p0, 8); pf[2] = pack_bf16x8(p1, 0); pf[3] = pack_bf16x8(p1, 8);
;             __builtin_amdgcn_sched_barrier(0);
; #pragma unroll
;             for (int d = 0; d < NDB; ++d) {
;                 if (d + 1 < NDB) {
; #pragma unroll
;                     for (int ks = 0; ks < 4; ++ks) vf[(d + 1) & 1][ks] = *(const LAS bf16x8*)(vb + (d + 1) * 32 * VROW + ks * 32);
;                 }
; #pragma unroll
;                 for (int ks = 0; ks < 4; ++ks) o[d] = __builtin_amdgcn_mfma_f32_32x32x16_bf16(vf[d & 1][ks], pf[ks], o[d], 0, 0, 0);
;                 __builtin_amdgcn_sched_barrier(0);
;             }
;         }
;         if (skip && more) ATT_GLOAD((FLAGS & AF_REV) ? t - 1 : t + 1);
;         if (more) ATT_LSTORE(cur ^ 1);
;         __syncthreads();
.LBB0_1281:
	v_exp_f32_e32 v116, v82
	v_exp_f32_e32 v118, v66
	v_exp_f32_e32 v117, v83
	v_exp_f32_e32 v119, v67
	v_exp_f32_e32 v120, v84
	v_exp_f32_e32 v122, v68
	v_exp_f32_e32 v121, v85
	v_exp_f32_e32 v123, v69
	v_exp_f32_e32 v124, v86
	v_exp_f32_e32 v126, v70
	v_exp_f32_e32 v125, v87
	v_exp_f32_e32 v127, v71
	v_exp_f32_e32 v128, v88
	v_exp_f32_e32 v130, v72
	v_exp_f32_e32 v129, v89
	v_exp_f32_e32 v131, v73
	v_exp_f32_e32 v132, v90
	v_exp_f32_e32 v134, v74
	v_exp_f32_e32 v133, v91
	v_exp_f32_e32 v135, v75
	v_exp_f32_e32 v136, v92
	v_exp_f32_e32 v138, v76
	v_exp_f32_e32 v137, v93
	v_exp_f32_e32 v139, v77
	v_exp_f32_e32 v140, v94
	v_exp_f32_e32 v142, v78
	v_exp_f32_e32 v141, v95
	v_exp_f32_e32 v143, v79
	v_exp_f32_e32 v144, v96
	v_exp_f32_e32 v148, v80
	v_exp_f32_e32 v145, v97
	v_exp_f32_e32 v149, v81
	s_add_u32 s2, s25, s14
	v_readlane_b32 s3, v252, 36
	s_addc_u32 s3, s3, s15
	s_add_u32 s6, s2, s37
	v_lshlrev_b64 v[114:115], 9, v[194:195]
	s_addc_u32 s7, s3, 0
	v_cvt_pk_bf16_f32 v66, v116, v117
	v_cvt_pk_bf16_f32 v67, v120, v121
	v_cvt_pk_bf16_f32 v68, v124, v125
	v_cvt_pk_bf16_f32 v69, v128, v129
	v_cvt_pk_bf16_f32 v70, v132, v133
	v_cvt_pk_bf16_f32 v71, v136, v137
	v_cvt_pk_bf16_f32 v72, v140, v141
	v_cvt_pk_bf16_f32 v73, v144, v145
	v_cvt_pk_bf16_f32 v74, v118, v119
	v_cvt_pk_bf16_f32 v75, v122, v123
	v_cvt_pk_bf16_f32 v76, v126, v127
	v_cvt_pk_bf16_f32 v77, v130, v131
	v_cvt_pk_bf16_f32 v78, v134, v135
	v_cvt_pk_bf16_f32 v79, v138, v139
	v_cvt_pk_bf16_f32 v80, v142, v143
	v_cvt_pk_bf16_f32 v81, v148, v149
	s_waitcnt lgkmcnt(3)
	v_mfma_f32_32x32x16_bf16 v[50:65], v[110:113], v[66:69], v[50:65]
	ds_read_b128 v[82:85], v0 offset:57856
	ds_read_b128 v[86:89], v0 offset:57888
	ds_read_b128 v[90:93], v0 offset:57920
	ds_read_b128 v[94:97], v0 offset:57952
	s_waitcnt lgkmcnt(6)
	v_mfma_f32_32x32x16_bf16 v[50:65], v[106:109], v[70:73], v[50:65]
	s_waitcnt lgkmcnt(5)
	v_mfma_f32_32x32x16_bf16 v[50:65], v[102:105], v[74:77], v[50:65]
	s_waitcnt lgkmcnt(4)
	v_mfma_f32_32x32x16_bf16 v[50:65], v[98:101], v[78:81], v[50:65]
	s_waitcnt lgkmcnt(3)
	v_mfma_f32_32x32x16_bf16 v[34:49], v[82:85], v[66:69], v[34:49]
	s_waitcnt lgkmcnt(2)
	v_mfma_f32_32x32x16_bf16 v[34:49], v[86:89], v[70:73], v[34:49]
	s_waitcnt lgkmcnt(1)
	v_mfma_f32_32x32x16_bf16 v[34:49], v[90:93], v[74:77], v[34:49]
	ds_read_b128 v[82:85], v0 offset:62464
	ds_read_b128 v[86:89], v0 offset:62496
	ds_read_b128 v[90:93], v0 offset:62528
	ds_read_b128 v[98:101], v0 offset:62560
	s_waitcnt lgkmcnt(4)
	v_mfma_f32_32x32x16_bf16 v[34:49], v[94:97], v[78:81], v[34:49]
	s_waitcnt lgkmcnt(3)
	v_mfma_f32_32x32x16_bf16 v[18:33], v[82:85], v[66:69], v[18:33]
	s_waitcnt lgkmcnt(2)
	v_mfma_f32_32x32x16_bf16 v[18:33], v[86:89], v[70:73], v[18:33]
	s_waitcnt lgkmcnt(1)
	v_mfma_f32_32x32x16_bf16 v[18:33], v[90:93], v[74:77], v[18:33]
	ds_read_b128 v[82:85], v211 offset:13824
	ds_read_b128 v[86:89], v211 offset:13856
	ds_read_b128 v[90:93], v211 offset:13888
	ds_read_b128 v[94:97], v211 offset:13920
	s_waitcnt lgkmcnt(4)
	v_mfma_f32_32x32x16_bf16 v[18:33], v[98:101], v[78:81], v[18:33]
	s_waitcnt lgkmcnt(3)
	v_mfma_f32_32x32x16_bf16 v[2:17], v[82:85], v[66:69], v[2:17]
	s_waitcnt lgkmcnt(2)
	v_mfma_f32_32x32x16_bf16 v[2:17], v[86:89], v[70:73], v[2:17]
	s_waitcnt lgkmcnt(1)
	v_mfma_f32_32x32x16_bf16 v[2:17], v[90:93], v[74:77], v[2:17]
	s_waitcnt lgkmcnt(0)
	v_mfma_f32_32x32x16_bf16 v[2:17], v[94:97], v[78:81], v[2:17]
	v_add_f32_e64 v66, v116, 0
	v_add_f32_e64 v67, v117, 0
	v_add_f32_e64 v66, v118, v66
	v_add_f32_e64 v67, v119, v67
	v_pk_add_f32 v[66:67], v[120:121], v[66:67]
	s_nop 0
	v_pk_add_f32 v[66:67], v[122:123], v[66:67]
	s_nop 0
	v_pk_add_f32 v[66:67], v[124:125], v[66:67]
	s_nop 0
	v_pk_add_f32 v[66:67], v[126:127], v[66:67]
	s_nop 0
	v_pk_add_f32 v[66:67], v[128:129], v[66:67]
	s_nop 0
	v_pk_add_f32 v[66:67], v[130:131], v[66:67]
	s_nop 0
	v_pk_add_f32 v[66:67], v[132:133], v[66:67]
	s_nop 0
	v_pk_add_f32 v[66:67], v[134:135], v[66:67]
	s_nop 0
	v_pk_add_f32 v[66:67], v[136:137], v[66:67]
	s_nop 0
	v_pk_add_f32 v[66:67], v[138:139], v[66:67]
	s_nop 0
	v_pk_add_f32 v[66:67], v[140:141], v[66:67]
	s_nop 0
	v_pk_add_f32 v[66:67], v[142:143], v[66:67]
	s_nop 0
	v_pk_add_f32 v[66:67], v[144:145], v[66:67]
	s_nop 0
	v_pk_add_f32 v[66:67], v[148:149], v[66:67]
	s_nop 0
	v_add_f32_e32 v0, v66, v67
	v_add_f32_e32 v0, v146, v0
	ds_bpermute_b32 v66, v205, v0
	s_waitcnt lgkmcnt(0)
; __device__ __forceinline__ unsigned pk2(float lo, float hi) { f32x2 v = {lo, hi}; bf16x2_t b = __builtin_convertvector(v, bf16x2_t); return __builtin_bit_cast(unsigned, b); }
; __device__ __forceinline__ float shfl_xor_l(float v, int o, int lane) { return __builtin_bit_cast(float, __builtin_amdgcn_ds_bpermute((lane ^ o) << 2, __builtin_bit_cast(int, v))); }
; template <int DQK, int DV, int FLAGS, int qp, int kp, int vts, int op> ...
;     ...
;     float lt = l + shfl_xor_l(l, 32, lane);
;     if (FLAGS & AF_SINK) lt += __builtin_amdgcn_exp2f(sink2 - m);
;     const float inv = 1.0f / lt;
;     bf16* orow = O + (size_t)(32 * wave + r32) * op + 4 * hi;
; #pragma unroll
;     for (int d = 0; d < NDB; ++d)
; #pragma unroll
;         for (int g = 0; g < 4; ++g) {
;             u32x2 w; w.x = pk2(o[d][4 * g] * inv, o[d][4 * g + 1] * inv); w.y = pk2(o[d][4 * g + 2] * inv, o[d][4 * g + 3] * inv);
;             *(u32x2*)(orow + 32 * d + 8 * g) = w;
;         }
	v_add_f32_e32 v0, v0, v66
	v_div_scale_f32 v66, s[2:3], v0, v0, 1.0
	v_rcp_f32_e32 v67, v66
	v_div_scale_f32 v68, vcc, 1.0, v0, 1.0
	v_readlane_b32 s2, v252, 18
	v_fma_f32 v69, -v66, v67, 1.0
	v_fmac_f32_e32 v67, v69, v67
	v_mul_f32_e32 v69, v68, v67
	v_fma_f32 v70, -v66, v69, v68
	v_fmac_f32_e32 v69, v70, v67
	v_fma_f32 v66, -v66, v69, v68
	v_div_fmas_f32 v66, v66, v67, v69
	v_div_fixup_f32 v66, v66, v0, 1.0
	v_lshl_add_u64 v[68:69], v[114:115], 1, s[6:7]
	v_lshlrev_b32_e32 v0, 3, v204
	v_lshl_add_u64 v[68:69], v[68:69], 0, v[0:1]
	v_lshl_add_u64 v[68:69], v[68:69], 0, v[0:1]
	v_pk_mul_f32 v[50:51], v[50:51], v[66:67] op_sel_hi:[1,0]
	v_pk_mul_f32 v[52:53], v[52:53], v[66:67] op_sel_hi:[1,0]
	v_pk_mul_f32 v[54:55], v[54:55], v[66:67] op_sel_hi:[1,0]
	v_pk_mul_f32 v[56:57], v[56:57], v[66:67] op_sel_hi:[1,0]
	v_cvt_pk_bf16_f32 v240, v50, v51
	v_cvt_pk_bf16_f32 v241, v52, v53
	v_cvt_pk_bf16_f32 v242, v54, v55
	v_cvt_pk_bf16_f32 v243, v56, v57
	s_nop 1
	v_permlane32_swap_b32 v240, v242
	v_permlane32_swap_b32 v241, v243
	global_store_dwordx4 v[68:69], v[240:243], off
	v_pk_mul_f32 v[58:59], v[58:59], v[66:67] op_sel_hi:[1,0]
	v_pk_mul_f32 v[60:61], v[60:61], v[66:67] op_sel_hi:[1,0]
	v_pk_mul_f32 v[62:63], v[62:63], v[66:67] op_sel_hi:[1,0]
	v_pk_mul_f32 v[64:65], v[64:65], v[66:67] op_sel_hi:[1,0]
	v_cvt_pk_bf16_f32 v240, v58, v59
	v_cvt_pk_bf16_f32 v241, v60, v61
	v_cvt_pk_bf16_f32 v242, v62, v63
	v_cvt_pk_bf16_f32 v243, v64, v65
	s_nop 1
	v_permlane32_swap_b32 v240, v242
	v_permlane32_swap_b32 v241, v243
	global_store_dwordx4 v[68:69], v[240:243], off offset:32
	v_pk_mul_f32 v[34:35], v[34:35], v[66:67] op_sel_hi:[1,0]
	v_pk_mul_f32 v[36:37], v[36:37], v[66:67] op_sel_hi:[1,0]
	v_pk_mul_f32 v[38:39], v[38:39], v[66:67] op_sel_hi:[1,0]
	v_pk_mul_f32 v[40:41], v[40:41], v[66:67] op_sel_hi:[1,0]
	v_cvt_pk_bf16_f32 v240, v34, v35
	v_cvt_pk_bf16_f32 v241, v36, v37
	v_cvt_pk_bf16_f32 v242, v38, v39
	v_cvt_pk_bf16_f32 v243, v40, v41
	s_nop 1
	v_permlane32_swap_b32 v240, v242
	v_permlane32_swap_b32 v241, v243
	global_store_dwordx4 v[68:69], v[240:243], off offset:64
	v_pk_mul_f32 v[42:43], v[42:43], v[66:67] op_sel_hi:[1,0]
	v_pk_mul_f32 v[44:45], v[44:45], v[66:67] op_sel_hi:[1,0]
	v_pk_mul_f32 v[46:47], v[46:47], v[66:67] op_sel_hi:[1,0]
	v_pk_mul_f32 v[48:49], v[48:49], v[66:67] op_sel_hi:[1,0]
	v_cvt_pk_bf16_f32 v240, v42, v43
	v_cvt_pk_bf16_f32 v241, v44, v45
	v_cvt_pk_bf16_f32 v242, v46, v47
	v_cvt_pk_bf16_f32 v243, v48, v49
	s_nop 1
	v_permlane32_swap_b32 v240, v242
	v_permlane32_swap_b32 v241, v243
	global_store_dwordx4 v[68:69], v[240:243], off offset:96
	v_pk_mul_f32 v[18:19], v[18:19], v[66:67] op_sel_hi:[1,0]
	v_pk_mul_f32 v[20:21], v[20:21], v[66:67] op_sel_hi:[1,0]
	v_pk_mul_f32 v[22:23], v[22:23], v[66:67] op_sel_hi:[1,0]
	v_pk_mul_f32 v[24:25], v[24:25], v[66:67] op_sel_hi:[1,0]
	v_cvt_pk_bf16_f32 v240, v18, v19
	v_cvt_pk_bf16_f32 v241, v20, v21
	v_cvt_pk_bf16_f32 v242, v22, v23
	v_cvt_pk_bf16_f32 v243, v24, v25
	s_nop 1
	v_permlane32_swap_b32 v240, v242
	v_permlane32_swap_b32 v241, v243
	global_store_dwordx4 v[68:69], v[240:243], off offset:128
	v_pk_mul_f32 v[26:27], v[26:27], v[66:67] op_sel_hi:[1,0]
	v_pk_mul_f32 v[28:29], v[28:29], v[66:67] op_sel_hi:[1,0]
	v_pk_mul_f32 v[30:31], v[30:31], v[66:67] op_sel_hi:[1,0]
	v_pk_mul_f32 v[32:33], v[32:33], v[66:67] op_sel_hi:[1,0]
	v_cvt_pk_bf16_f32 v240, v26, v27
	v_cvt_pk_bf16_f32 v241, v28, v29
	v_cvt_pk_bf16_f32 v242, v30, v31
	v_cvt_pk_bf16_f32 v243, v32, v33
	s_nop 1
	v_permlane32_swap_b32 v240, v242
	v_permlane32_swap_b32 v241, v243
	global_store_dwordx4 v[68:69], v[240:243], off offset:160
	v_pk_mul_f32 v[2:3], v[2:3], v[66:67] op_sel_hi:[1,0]
	v_pk_mul_f32 v[4:5], v[4:5], v[66:67] op_sel_hi:[1,0]
	v_pk_mul_f32 v[6:7], v[6:7], v[66:67] op_sel_hi:[1,0]
	v_pk_mul_f32 v[8:9], v[8:9], v[66:67] op_sel_hi:[1,0]
	v_cvt_pk_bf16_f32 v240, v2, v3
	v_cvt_pk_bf16_f32 v241, v4, v5
	v_cvt_pk_bf16_f32 v242, v6, v7
	v_cvt_pk_bf16_f32 v243, v8, v9
	s_nop 1
	v_permlane32_swap_b32 v240, v242
	v_permlane32_swap_b32 v241, v243
	global_store_dwordx4 v[68:69], v[240:243], off offset:192
	v_pk_mul_f32 v[10:11], v[10:11], v[66:67] op_sel_hi:[1,0]
	v_pk_mul_f32 v[12:13], v[12:13], v[66:67] op_sel_hi:[1,0]
	v_pk_mul_f32 v[14:15], v[14:15], v[66:67] op_sel_hi:[1,0]
	v_pk_mul_f32 v[16:17], v[16:17], v[66:67] op_sel_hi:[1,0]
	v_cvt_pk_bf16_f32 v240, v10, v11
	v_cvt_pk_bf16_f32 v241, v12, v13
	v_cvt_pk_bf16_f32 v242, v14, v15
	v_cvt_pk_bf16_f32 v243, v16, v17
	s_nop 1
	v_permlane32_swap_b32 v240, v242
	v_permlane32_swap_b32 v241, v243
	global_store_dwordx4 v[68:69], v[240:243], off offset:224
	v_readlane_b32 s3, v252, 19
	s_load_dword s2, s[2:3], 0x0
	s_waitcnt lgkmcnt(0)
	s_add_i32 s36, s2, s36
	s_cmpk_lt_i32 s36, 0x200
	s_cbranch_scc0 .LBB0_1288
